# EpiRes epilogues (out-proj, down L0): per-column parameter load ladder de-serialised - 12 loads issued together, one wait, same math
# baseline (speedup 1.0000x reference)
.LBB0_1057:
	v_lshl_or_b32 v168, s27, 8, v198
	s_lshl_b64 s[0:1], s[0:1], 2
	s_add_u32 s0, s37, s0
	v_ashrrev_i32_e32 v169, 31, v168
	s_addc_u32 s1, s39, s1
	v_lshlrev_b64 v[66:67], 2, v[168:169]
	v_lshl_add_u64 v[64:65], s[0:1], 0, v[66:67]
	v_add_co_u32_e32 v68, vcc, 0x2000, v64
	v_readlane_b32 s24, v254, 34
	s_nop 0
	v_addc_co_u32_e32 v69, vcc, 0, v65, vcc
	v_readlane_b32 s25, v254, 35
	v_lshl_add_u64 v[182:183], s[10:11], 0, v[66:67]
	s_andn2_b64 vcc, exec, s[24:25]
	v_cndmask_b32_e64 v66, 0, 1, s[24:25]
	s_mov_b64 s[24:25], 0x4000
	v_cmp_ne_u32_e64 s[0:1], 1, v66
	v_lshl_add_u64 v[188:189], v[64:65], 0, s[24:25]
	global_load_dwordx4 v[72:75], v[68:69], off
	global_load_dwordx4 v[80:83], v[68:69], off offset:16
	global_load_dwordx4 v[64:67], v[68:69], off offset:512
	global_load_dwordx4 v[68:71], v[68:69], off offset:528
	s_cbranch_vccnz .Lpl_op_noxn
	global_load_dwordx4 v[208:211], v[188:189], off
	global_load_dwordx4 v[212:215], v[188:189], off offset:16
	global_load_dwordx4 v[216:219], v[188:189], off offset:512
	global_load_dwordx4 v[220:223], v[188:189], off offset:528
	global_load_dwordx4 v[174:177], v[182:183], off
	global_load_dwordx4 v[184:187], v[182:183], off offset:16
	global_load_dwordx4 v[170:173], v[182:183], off offset:512
	global_load_dwordx4 v[178:181], v[182:183], off offset:528
	s_waitcnt vmcnt(0)
	v_pk_add_f32 v[210:211], v[210:211], 1.0 op_sel_hi:[1,0]
	v_pk_add_f32 v[208:209], v[208:209], 1.0 op_sel_hi:[1,0]
	v_pk_mul_f32 v[176:177], v[176:177], v[210:211]
	v_pk_mul_f32 v[174:175], v[174:175], v[208:209]
	v_pk_add_f32 v[214:215], v[214:215], 1.0 op_sel_hi:[1,0]
	v_pk_add_f32 v[212:213], v[212:213], 1.0 op_sel_hi:[1,0]
	v_pk_mul_f32 v[186:187], v[186:187], v[214:215]
	v_pk_mul_f32 v[184:185], v[184:185], v[212:213]
	v_pk_add_f32 v[218:219], v[218:219], 1.0 op_sel_hi:[1,0]
	v_pk_add_f32 v[216:217], v[216:217], 1.0 op_sel_hi:[1,0]
	v_pk_mul_f32 v[172:173], v[172:173], v[218:219]
	v_pk_mul_f32 v[170:171], v[170:171], v[216:217]
	v_pk_add_f32 v[222:223], v[222:223], 1.0 op_sel_hi:[1,0]
	v_pk_add_f32 v[220:221], v[220:221], 1.0 op_sel_hi:[1,0]
	v_pk_mul_f32 v[180:181], v[180:181], v[222:223]
	v_pk_mul_f32 v[178:179], v[178:179], v[220:221]
.Lpl_op_noxn:
	s_waitcnt vmcnt(0)
.LBB0_1065:
	v_mbcnt_lo_u32_b32 v200, -1, 0
	v_mbcnt_hi_u32_b32 v200, -1, v200
	v_and_b32_e32 v201, 15, v200
	v_lshrrev_b32_e32 v182, 2, v200
	v_sub_u32_e32 v201, v182, v201
	v_add_u32_e32 v201, v196, v201
	v_lshrrev_b32_e32 v169, 4, v200
	v_and_b32_e32 v194, 3, v200
	v_sub_u32_e32 v169, v194, v169
	v_lshl_add_u32 v169, v169, 3, v198
	v_lshl_or_b32 v168, s27, 8, v169
	v_lshl_add_u32 v195, v194, 4, v182
	v_lshlrev_b32_e32 v195, 2, v195
	v_xor_b32_e32 v188, 1, v200
	v_lshlrev_b32_e32 v188, 2, v188
	v_xor_b32_e32 v200, 2, v200
	v_lshlrev_b32_e32 v200, 2, v200
	ds_bpermute_b32 v208, v195, v72
	ds_bpermute_b32 v209, v195, v73
	ds_bpermute_b32 v210, v195, v74
	ds_bpermute_b32 v211, v195, v75
	ds_bpermute_b32 v212, v195, v80
	ds_bpermute_b32 v213, v195, v81
	ds_bpermute_b32 v214, v195, v82
	ds_bpermute_b32 v215, v195, v83
	s_waitcnt lgkmcnt(7)
	ds_bpermute_b32 v216, v195, v64
	ds_bpermute_b32 v217, v195, v65
	ds_bpermute_b32 v218, v195, v66
	ds_bpermute_b32 v219, v195, v67
	ds_bpermute_b32 v220, v195, v68
	ds_bpermute_b32 v221, v195, v69
	ds_bpermute_b32 v222, v195, v70
	ds_bpermute_b32 v223, v195, v71
	s_waitcnt lgkmcnt(0)
	v_mov_b64_e32 v[72:73], v[208:209]
	v_mov_b64_e32 v[74:75], v[210:211]
	v_mov_b64_e32 v[80:81], v[212:213]
	v_mov_b64_e32 v[82:83], v[214:215]
	v_mov_b64_e32 v[64:65], v[216:217]
	v_mov_b64_e32 v[66:67], v[218:219]
	v_mov_b64_e32 v[68:69], v[220:221]
	v_mov_b64_e32 v[70:71], v[222:223]
	ds_bpermute_b32 v154, v195, v174
	ds_bpermute_b32 v155, v195, v175
	ds_bpermute_b32 v156, v195, v176
	ds_bpermute_b32 v157, v195, v177
	ds_bpermute_b32 v158, v195, v184
	ds_bpermute_b32 v159, v195, v185
	ds_bpermute_b32 v160, v195, v186
	ds_bpermute_b32 v161, v195, v187
	s_waitcnt lgkmcnt(7)
	ds_bpermute_b32 v162, v195, v170
	ds_bpermute_b32 v163, v195, v171
	ds_bpermute_b32 v164, v195, v172
	ds_bpermute_b32 v165, v195, v173
	ds_bpermute_b32 v224, v195, v178
	ds_bpermute_b32 v225, v195, v179
	ds_bpermute_b32 v226, v195, v180
	ds_bpermute_b32 v227, v195, v181
	s_waitcnt lgkmcnt(0)
	v_mov_b64_e32 v[174:175], v[154:155]
	v_mov_b64_e32 v[176:177], v[156:157]
	v_mov_b64_e32 v[184:185], v[158:159]
	v_mov_b64_e32 v[186:187], v[160:161]
	v_mov_b64_e32 v[170:171], v[162:163]
	v_mov_b64_e32 v[172:173], v[164:165]
	v_mov_b64_e32 v[178:179], v[224:225]
	v_mov_b64_e32 v[180:181], v[226:227]
	ds_bpermute_b32 v154, v195, v124
	ds_bpermute_b32 v155, v195, v125
	ds_bpermute_b32 v156, v195, v126
	ds_bpermute_b32 v157, v195, v127
	ds_bpermute_b32 v158, v195, v120
	ds_bpermute_b32 v159, v195, v121
	ds_bpermute_b32 v160, v195, v122
	ds_bpermute_b32 v161, v195, v123
	s_waitcnt lgkmcnt(7)
	ds_bpermute_b32 v162, v195, v116
	ds_bpermute_b32 v163, v195, v117
	ds_bpermute_b32 v164, v195, v118
	ds_bpermute_b32 v165, v195, v119
	ds_bpermute_b32 v224, v195, v112
	ds_bpermute_b32 v225, v195, v113
	ds_bpermute_b32 v226, v195, v114
	ds_bpermute_b32 v227, v195, v115
	s_lshl_b32 s15, s26, 8
	s_add_i32 s17, s15, 0xffff8000
	s_and_b64 s[22:23], s[22:23], exec
	s_cselect_b32 s17, s15, s17
	s_cselect_b32 s23, s35, s56
	s_cselect_b32 s22, s53, s94
	v_readlane_b32 s100, v253, 59
	s_nop 0
	s_cselect_b32 s25, s75, s100
	v_readlane_b32 s100, v253, 58
	s_nop 0
	s_cselect_b32 s24, s74, s100
	v_readlane_b32 s26, v254, 49
	v_readlane_b32 s27, v254, 50
	v_add_u32_e32 v189, s17, v201
	v_lshl_add_u32 v189, v189, 10, v168
	v_lshlrev_b32_e32 v189, 2, v189
	v_add_u32_e32 v191, s15, v201
	v_lshl_add_u32 v190, v191, 10, v168
	v_lshlrev_b32_e32 v190, 1, v190
	v_lshlrev_b32_e32 v191, 2, v191
	v_cmp_eq_u32_e32 vcc, 0, v194
	s_waitcnt vmcnt(0)
	s_waitcnt lgkmcnt(0)
	ds_bpermute_b32 v208, v195, v140
	ds_bpermute_b32 v209, v195, v141
	ds_bpermute_b32 v210, v195, v142
	ds_bpermute_b32 v211, v195, v143
	ds_bpermute_b32 v212, v195, v136
	ds_bpermute_b32 v213, v195, v137
	ds_bpermute_b32 v214, v195, v138
	ds_bpermute_b32 v215, v195, v139
	s_waitcnt lgkmcnt(7)
	ds_bpermute_b32 v216, v195, v132
	ds_bpermute_b32 v217, v195, v133
	ds_bpermute_b32 v218, v195, v134
	ds_bpermute_b32 v219, v195, v135
	ds_bpermute_b32 v220, v195, v128
	ds_bpermute_b32 v221, v195, v129
	ds_bpermute_b32 v222, v195, v130
	ds_bpermute_b32 v223, v195, v131
	s_waitcnt lgkmcnt(0)
	global_load_dwordx4 v[140:143], v189, s[22:23]
	global_load_dwordx4 v[136:139], v189, s[22:23] offset:16
	global_load_dwordx4 v[132:135], v189, s[22:23] offset:512
	global_load_dwordx4 v[128:131], v189, s[22:23] offset:528
	s_add_u32 s22, s22, 0x10000
	s_addc_u32 s23, s23, 0
	global_load_dwordx4 v[124:127], v189, s[22:23]
	global_load_dwordx4 v[120:123], v189, s[22:23] offset:16
	global_load_dwordx4 v[116:119], v189, s[22:23] offset:512
	global_load_dwordx4 v[112:115], v189, s[22:23] offset:528
	s_add_u32 s22, s22, 0x10000
	s_addc_u32 s23, s23, 0
	s_waitcnt vmcnt(4)
	v_pk_fma_f32 v[140:141], v[208:209], v[72:73], v[140:141]
	v_pk_fma_f32 v[142:143], v[210:211], v[74:75], v[142:143]
	v_pk_fma_f32 v[136:137], v[212:213], v[80:81], v[136:137]
	v_pk_fma_f32 v[138:139], v[214:215], v[82:83], v[138:139]
	v_pk_fma_f32 v[132:133], v[216:217], v[64:65], v[132:133]
	v_pk_fma_f32 v[134:135], v[218:219], v[66:67], v[134:135]
	v_pk_fma_f32 v[128:129], v[220:221], v[68:69], v[128:129]
	v_pk_fma_f32 v[130:131], v[222:223], v[70:71], v[130:131]
	ds_bpermute_b32 v208, v195, v108
	ds_bpermute_b32 v209, v195, v109
	ds_bpermute_b32 v210, v195, v110
	ds_bpermute_b32 v211, v195, v111
	ds_bpermute_b32 v212, v195, v104
	ds_bpermute_b32 v213, v195, v105
	ds_bpermute_b32 v214, v195, v106
	ds_bpermute_b32 v215, v195, v107
	global_store_dwordx4 v189, v[140:143], s[24:25]
	global_store_dwordx4 v189, v[136:139], s[24:25] offset:16
	global_store_dwordx4 v189, v[132:135], s[24:25] offset:512
	global_store_dwordx4 v189, v[128:131], s[24:25] offset:528
	s_add_u32 s24, s24, 0x10000
	s_addc_u32 s25, s25, 0
	s_waitcnt lgkmcnt(6)
	ds_bpermute_b32 v216, v195, v100
	ds_bpermute_b32 v217, v195, v101
	ds_bpermute_b32 v218, v195, v102
	ds_bpermute_b32 v219, v195, v103
	ds_bpermute_b32 v220, v195, v96
	ds_bpermute_b32 v221, v195, v97
	ds_bpermute_b32 v222, v195, v98
	ds_bpermute_b32 v223, v195, v99
	v_pk_mul_f32 v[168:169], v[140:141], v[140:141]
	v_pk_fma_f32 v[168:169], v[142:143], v[142:143], v[168:169]
	v_pk_fma_f32 v[168:169], v[136:137], v[136:137], v[168:169]
	v_pk_fma_f32 v[168:169], v[138:139], v[138:139], v[168:169]
	v_pk_fma_f32 v[168:169], v[132:133], v[132:133], v[168:169]
	v_pk_fma_f32 v[168:169], v[134:135], v[134:135], v[168:169]
	v_pk_fma_f32 v[168:169], v[128:129], v[128:129], v[168:169]
	v_pk_fma_f32 v[168:169], v[130:131], v[130:131], v[168:169]
	v_add_f32_e32 v193, v168, v169
	ds_bpermute_b32 v192, v188, v193
	v_pk_mul_f32 v[140:141], v[174:175], v[140:141]
	v_pk_mul_f32 v[142:143], v[176:177], v[142:143]
	v_pk_mul_f32 v[136:137], v[184:185], v[136:137]
	v_pk_mul_f32 v[138:139], v[186:187], v[138:139]
	v_pk_mul_f32 v[132:133], v[170:171], v[132:133]
	v_pk_mul_f32 v[134:135], v[172:173], v[134:135]
	v_pk_mul_f32 v[128:129], v[178:179], v[128:129]
	v_pk_mul_f32 v[130:131], v[180:181], v[130:131]
	s_waitcnt lgkmcnt(0)
	v_add_f32_e32 v193, v193, v192
	ds_bpermute_b32 v192, v200, v193
	v_cvt_pk_bf16_f32 v140, v140, v141
	v_cvt_pk_bf16_f32 v141, v142, v143
	v_cvt_pk_bf16_f32 v142, v136, v137
	v_cvt_pk_bf16_f32 v143, v138, v139
	v_cvt_pk_bf16_f32 v132, v132, v133
	v_cvt_pk_bf16_f32 v133, v134, v135
	v_cvt_pk_bf16_f32 v134, v128, v129
	v_cvt_pk_bf16_f32 v135, v130, v131
	s_waitcnt lgkmcnt(0)
	v_add_f32_e32 v193, v193, v192
	global_store_dwordx4 v190, v[140:143], s[26:27]
	global_store_dwordx4 v190, v[132:135], s[26:27] offset:256
	s_add_u32 s26, s26, 0x8000
	s_addc_u32 s27, s27, 0
	s_and_saveexec_b64 s[100:101], vcc
	s_cbranch_execz .Lepit_op_na0
	global_atomic_add_f32 v191, v193, s[54:55]

.LBB0_1245:
	v_lshl_or_b32 v178, s9, 8, v211
	s_lshl_b64 s[22:23], s[22:23], 2
	s_add_u32 s24, s37, s22
	v_ashrrev_i32_e32 v179, 31, v178
	s_addc_u32 s25, s39, s23
	v_lshlrev_b64 v[130:131], 2, v[178:179]
	v_lshl_add_u64 v[128:129], s[24:25], 0, v[130:131]
	v_readlane_b32 s24, v254, 38
	s_add_u32 s22, s76, s22
	v_readlane_b32 s25, v254, 39
	s_addc_u32 s23, s77, s23
	s_nop 0
	v_lshl_add_u64 v[144:145], s[24:25], 0, v[130:131]
	v_lshl_add_u64 v[130:131], s[22:23], 0, v[130:131]
	s_mov_b64 s[22:23], 0x1000
	v_lshl_add_u64 v[146:147], v[130:131], 0, s[22:23]
	v_add_co_u32_e32 v130, vcc, 0x5000, v128
	s_nop 1
	v_addc_co_u32_e32 v131, vcc, 0, v129, vcc
	global_load_dwordx4 v[136:139], v[130:131], off
	global_load_dwordx4 v[140:143], v[130:131], off offset:16
	global_load_dwordx4 v[132:135], v[130:131], off offset:528
	global_load_dwordx4 v[128:131], v[130:131], off offset:512
	s_and_b64 vcc, exec, s[0:1]
	s_cbranch_vccnz .Lpl_d0_noxn
	global_load_dwordx4 v[214:217], v[146:147], off
	global_load_dwordx4 v[218:221], v[146:147], off offset:16
	global_load_dwordx4 v[198:201], v[146:147], off offset:512
	global_load_dwordx4 v[178:181], v[146:147], off offset:528
	global_load_dwordx4 v[186:189], v[144:145], off
	global_load_dwordx4 v[194:197], v[144:145], off offset:16
	global_load_dwordx4 v[182:185], v[144:145], off offset:512
	global_load_dwordx4 v[190:193], v[144:145], off offset:528
	s_waitcnt vmcnt(0)
	v_pk_add_f32 v[216:217], v[216:217], 1.0 op_sel_hi:[1,0]
	v_pk_add_f32 v[214:215], v[214:215], 1.0 op_sel_hi:[1,0]
	v_pk_mul_f32 v[188:189], v[188:189], v[216:217]
	v_pk_mul_f32 v[186:187], v[186:187], v[214:215]
	v_pk_add_f32 v[220:221], v[220:221], 1.0 op_sel_hi:[1,0]
	v_pk_add_f32 v[218:219], v[218:219], 1.0 op_sel_hi:[1,0]
	v_pk_mul_f32 v[196:197], v[196:197], v[220:221]
	v_pk_mul_f32 v[194:195], v[194:195], v[218:219]
	v_pk_add_f32 v[200:201], v[200:201], 1.0 op_sel_hi:[1,0]
	v_pk_add_f32 v[198:199], v[198:199], 1.0 op_sel_hi:[1,0]
	v_pk_mul_f32 v[184:185], v[184:185], v[200:201]
	v_pk_mul_f32 v[182:183], v[182:183], v[198:199]
	v_pk_add_f32 v[180:181], v[180:181], 1.0 op_sel_hi:[1,0]
	v_pk_add_f32 v[178:179], v[178:179], 1.0 op_sel_hi:[1,0]
	v_pk_mul_f32 v[192:193], v[192:193], v[180:181]
	v_pk_mul_f32 v[190:191], v[190:191], v[178:179]
.Lpl_d0_noxn:
	s_waitcnt vmcnt(0)
.LBB0_1253:
	v_mbcnt_lo_u32_b32 v227, -1, 0
	v_mbcnt_hi_u32_b32 v227, -1, v227
	v_and_b32_e32 v232, 15, v227
	v_lshrrev_b32_e32 v233, 2, v227
	v_sub_u32_e32 v232, v233, v232
	v_add_u32_e32 v232, v208, v232
	v_lshrrev_b32_e32 v241, 4, v227
	v_and_b32_e32 v240, 3, v227
	v_sub_u32_e32 v241, v240, v241
	v_lshl_add_u32 v241, v241, 3, v211
	v_lshl_or_b32 v241, s9, 8, v241
	v_lshl_add_u32 v222, v240, 4, v233
	v_lshlrev_b32_e32 v222, 2, v222
	v_xor_b32_e32 v226, 1, v227
	v_lshlrev_b32_e32 v226, 2, v226
	v_xor_b32_e32 v227, 2, v227
	v_lshlrev_b32_e32 v227, 2, v227
	ds_bpermute_b32 v144, v222, v136
	ds_bpermute_b32 v145, v222, v137
	ds_bpermute_b32 v146, v222, v138
	ds_bpermute_b32 v147, v222, v139
	ds_bpermute_b32 v148, v222, v140
	ds_bpermute_b32 v149, v222, v141
	ds_bpermute_b32 v150, v222, v142
	ds_bpermute_b32 v151, v222, v143
	s_waitcnt lgkmcnt(7)
	ds_bpermute_b32 v154, v222, v128
	ds_bpermute_b32 v155, v222, v129
	ds_bpermute_b32 v156, v222, v130
	ds_bpermute_b32 v157, v222, v131
	ds_bpermute_b32 v158, v222, v132
	ds_bpermute_b32 v159, v222, v133
	ds_bpermute_b32 v160, v222, v134
	ds_bpermute_b32 v161, v222, v135
	s_waitcnt lgkmcnt(0)
	v_mov_b64_e32 v[136:137], v[144:145]
	v_mov_b64_e32 v[138:139], v[146:147]
	v_mov_b64_e32 v[140:141], v[148:149]
	v_mov_b64_e32 v[142:143], v[150:151]
	v_mov_b64_e32 v[128:129], v[154:155]
	v_mov_b64_e32 v[130:131], v[156:157]
	v_mov_b64_e32 v[132:133], v[158:159]
	v_mov_b64_e32 v[134:135], v[160:161]
	ds_bpermute_b32 v214, v222, v186
	ds_bpermute_b32 v215, v222, v187
	ds_bpermute_b32 v216, v222, v188
	ds_bpermute_b32 v217, v222, v189
	ds_bpermute_b32 v218, v222, v194
	ds_bpermute_b32 v219, v222, v195
	ds_bpermute_b32 v220, v222, v196
	ds_bpermute_b32 v221, v222, v197
	s_waitcnt lgkmcnt(7)
	ds_bpermute_b32 v198, v222, v182
	ds_bpermute_b32 v199, v222, v183
	ds_bpermute_b32 v200, v222, v184
	ds_bpermute_b32 v201, v222, v185
	ds_bpermute_b32 v178, v222, v190
	ds_bpermute_b32 v179, v222, v191
	ds_bpermute_b32 v180, v222, v192
	ds_bpermute_b32 v181, v222, v193
	s_waitcnt lgkmcnt(0)
	v_mov_b64_e32 v[186:187], v[214:215]
	v_mov_b64_e32 v[188:189], v[216:217]
	v_mov_b64_e32 v[194:195], v[218:219]
	v_mov_b64_e32 v[196:197], v[220:221]
	v_mov_b64_e32 v[182:183], v[198:199]
	v_mov_b64_e32 v[184:185], v[200:201]
	v_mov_b64_e32 v[190:191], v[178:179]
	v_mov_b64_e32 v[192:193], v[180:181]
	ds_bpermute_b32 v214, v222, v116
	ds_bpermute_b32 v215, v222, v117
	ds_bpermute_b32 v216, v222, v118
	ds_bpermute_b32 v217, v222, v119
	ds_bpermute_b32 v218, v222, v112
	ds_bpermute_b32 v219, v222, v113
	ds_bpermute_b32 v220, v222, v114
	ds_bpermute_b32 v221, v222, v115
	s_waitcnt lgkmcnt(7)
	ds_bpermute_b32 v198, v222, v92
	ds_bpermute_b32 v199, v222, v93
	ds_bpermute_b32 v200, v222, v94
	ds_bpermute_b32 v201, v222, v95
	ds_bpermute_b32 v178, v222, v84
	ds_bpermute_b32 v179, v222, v85
	ds_bpermute_b32 v180, v222, v86
	ds_bpermute_b32 v181, v222, v87
	s_lshl_b32 s11, s54, 8
	s_add_i32 s13, s11, 0xffff8000
	s_and_b64 s[20:21], s[20:21], exec
	s_cselect_b32 s13, s11, s13
	v_readlane_b32 s100, v253, 59
	s_nop 0
	s_cselect_b32 s21, s75, s100
	v_readlane_b32 s100, v253, 58
	s_nop 0
	s_cselect_b32 s20, s74, s100
	s_mov_b64 s[100:101], s[20:21]
	v_readlane_b32 s22, v254, 49
	v_readlane_b32 s23, v254, 50
	v_readlane_b32 s24, v254, 6
	v_readlane_b32 s25, v254, 7
	v_add_u32_e32 v223, s13, v232
	v_lshl_add_u32 v223, v223, 10, v241
	v_lshlrev_b32_e32 v223, 2, v223
	v_add_u32_e32 v225, s11, v232
	v_lshl_add_u32 v224, v225, 10, v241
	v_lshlrev_b32_e32 v224, 1, v224
	v_lshlrev_b32_e32 v225, 2, v225
	v_cmp_eq_u32_e32 vcc, 0, v240
	s_waitcnt vmcnt(0)
	s_waitcnt lgkmcnt(0)
	ds_bpermute_b32 v144, v222, v124
	ds_bpermute_b32 v145, v222, v125
	ds_bpermute_b32 v146, v222, v126
	ds_bpermute_b32 v147, v222, v127
	ds_bpermute_b32 v148, v222, v120
	ds_bpermute_b32 v149, v222, v121
	ds_bpermute_b32 v150, v222, v122
	ds_bpermute_b32 v151, v222, v123
	s_waitcnt lgkmcnt(7)
	ds_bpermute_b32 v154, v222, v108
	ds_bpermute_b32 v155, v222, v109
	ds_bpermute_b32 v156, v222, v110
	ds_bpermute_b32 v157, v222, v111
	ds_bpermute_b32 v158, v222, v100
	ds_bpermute_b32 v159, v222, v101
	ds_bpermute_b32 v160, v222, v102
	ds_bpermute_b32 v161, v222, v103
	s_waitcnt lgkmcnt(0)
	global_load_dwordx4 v[124:127], v223, s[100:101]
	global_load_dwordx4 v[120:123], v223, s[100:101] offset:16
	global_load_dwordx4 v[108:111], v223, s[100:101] offset:512
	global_load_dwordx4 v[100:103], v223, s[100:101] offset:528
	s_add_u32 s100, s100, 0x10000
	s_addc_u32 s101, s101, 0
	global_load_dwordx4 v[116:119], v223, s[100:101]
	global_load_dwordx4 v[112:115], v223, s[100:101] offset:16
	global_load_dwordx4 v[92:95], v223, s[100:101] offset:512
	global_load_dwordx4 v[84:87], v223, s[100:101] offset:528
	s_add_u32 s100, s100, 0x10000
	s_addc_u32 s101, s101, 0
	s_waitcnt vmcnt(4)
	v_pk_fma_f32 v[124:125], v[144:145], v[136:137], v[124:125]
	v_pk_fma_f32 v[126:127], v[146:147], v[138:139], v[126:127]
	v_pk_fma_f32 v[120:121], v[148:149], v[140:141], v[120:121]
	v_pk_fma_f32 v[122:123], v[150:151], v[142:143], v[122:123]
	v_pk_fma_f32 v[108:109], v[154:155], v[128:129], v[108:109]
	v_pk_fma_f32 v[110:111], v[156:157], v[130:131], v[110:111]
	v_pk_fma_f32 v[100:101], v[158:159], v[132:133], v[100:101]
	v_pk_fma_f32 v[102:103], v[160:161], v[134:135], v[102:103]
	ds_bpermute_b32 v144, v222, v104
	ds_bpermute_b32 v145, v222, v105
	ds_bpermute_b32 v146, v222, v106
	ds_bpermute_b32 v147, v222, v107
	ds_bpermute_b32 v148, v222, v96
	ds_bpermute_b32 v149, v222, v97
	ds_bpermute_b32 v150, v222, v98
	ds_bpermute_b32 v151, v222, v99
	global_store_dwordx4 v223, v[124:127], s[20:21]
	global_store_dwordx4 v223, v[120:123], s[20:21] offset:16
	global_store_dwordx4 v223, v[108:111], s[20:21] offset:512
	global_store_dwordx4 v223, v[100:103], s[20:21] offset:528
	s_add_u32 s20, s20, 0x10000
	s_addc_u32 s21, s21, 0
	s_waitcnt lgkmcnt(6)
	ds_bpermute_b32 v154, v222, v76
	ds_bpermute_b32 v155, v222, v77
	ds_bpermute_b32 v156, v222, v78
	ds_bpermute_b32 v157, v222, v79
	ds_bpermute_b32 v158, v222, v72
	ds_bpermute_b32 v159, v222, v73
	ds_bpermute_b32 v160, v222, v74
	ds_bpermute_b32 v161, v222, v75
	v_pk_mul_f32 v[240:241], v[124:125], v[124:125]
	v_pk_fma_f32 v[240:241], v[126:127], v[126:127], v[240:241]
	v_pk_fma_f32 v[240:241], v[120:121], v[120:121], v[240:241]
	v_pk_fma_f32 v[240:241], v[122:123], v[122:123], v[240:241]
	v_pk_fma_f32 v[240:241], v[108:109], v[108:109], v[240:241]
	v_pk_fma_f32 v[240:241], v[110:111], v[110:111], v[240:241]
	v_pk_fma_f32 v[240:241], v[100:101], v[100:101], v[240:241]
	v_pk_fma_f32 v[240:241], v[102:103], v[102:103], v[240:241]
	v_add_f32_e32 v232, v240, v241
	ds_bpermute_b32 v233, v226, v232
	v_pk_mul_f32 v[124:125], v[186:187], v[124:125]
	v_pk_mul_f32 v[126:127], v[188:189], v[126:127]
	v_pk_mul_f32 v[120:121], v[194:195], v[120:121]
	v_pk_mul_f32 v[122:123], v[196:197], v[122:123]
	v_pk_mul_f32 v[108:109], v[182:183], v[108:109]
	v_pk_mul_f32 v[110:111], v[184:185], v[110:111]
	v_pk_mul_f32 v[100:101], v[190:191], v[100:101]
	v_pk_mul_f32 v[102:103], v[192:193], v[102:103]
	s_waitcnt lgkmcnt(0)
	v_add_f32_e32 v232, v232, v233
	ds_bpermute_b32 v233, v227, v232
	v_cvt_pk_bf16_f32 v124, v124, v125
	v_cvt_pk_bf16_f32 v125, v126, v127
	v_cvt_pk_bf16_f32 v126, v120, v121
	v_cvt_pk_bf16_f32 v127, v122, v123
	v_cvt_pk_bf16_f32 v108, v108, v109
	v_cvt_pk_bf16_f32 v109, v110, v111
	v_cvt_pk_bf16_f32 v110, v100, v101
	v_cvt_pk_bf16_f32 v111, v102, v103
	s_waitcnt lgkmcnt(0)
	v_add_f32_e32 v232, v232, v233
	global_store_dwordx4 v224, v[124:127], s[22:23]
	global_store_dwordx4 v224, v[108:111], s[22:23] offset:256
	s_add_u32 s22, s22, 0x8000
	s_addc_u32 s23, s23, 0
	s_mov_b64 exec, vcc
	s_cbranch_execz .Lepit_d0_na0
	global_atomic_add_f32 v225, v232, s[24:25]
